# dilated unit rewritten: K double-buffered in LDS and prefetched one unit ahead with the next unit's Q; V DMA hidden behind a two-phase compute (exact two-pass softmax); +16 KiB static LDS for V tiles
# baseline (speedup 1.0000x reference)
.LBB0_420:
	s_or_b64 exec, exec, s[4:5]
	s_add_u32 s4, s24, 0x18000000
	s_addc_u32 s5, s25, 0
	s_add_u32 s6, s24, 0x1e000000
	s_addc_u32 s7, s25, 0
	s_add_i32 s64, 0, 0x20140
	v_mov_b32_e32 v0, s64
	s_add_i32 s10, 0, 0x20144
	s_waitcnt lgkmcnt(0)
	s_barrier
	ds_read_b32 v0, v0
	v_mov_b32_e32 v1, s10
	ds_read_b32 v1, v1
	s_mov_b32 s11, 0
	s_waitcnt lgkmcnt(0)
	v_readfirstlane_b32 s19, v0
	s_cmpk_gt_i32 s19, 0x1ff
	v_readfirstlane_b32 s65, v1
	s_barrier
	s_cbranch_scc1 .LBB0_543
	s_lshl_b32 s18, s18, 1
	s_add_u32 s40, s16, s18
	s_addc_u32 s41, s17, 0
	s_add_u32 s42, s4, s18
	s_addc_u32 s43, s5, 0
	s_mul_i32 s10, s39, 0xc0
	s_add_u32 s12, s12, s10
	s_addc_u32 s13, s13, 0
	s_add_u32 s44, s44, s46
	s_addc_u32 s45, s45, 0
	s_lshl_b32 s10, s39, 2
	s_add_u32 s46, s6, s10
	s_addc_u32 s47, s7, 0
	s_add_u32 s48, s30, s18
	s_addc_u32 s49, s31, 0
	v_mov_b32_e32 v1, 0
	s_mov_b32 s100, -1
	s_mov_b32 s101, 0
	s_movk_i32 s66, 0x1800
	s_movk_i32 s67, 0xc00
	s_movk_i32 s68, 0xff
	s_movk_i32 s69, 0xbf
	s_movk_i32 s70, 0x1c0
	s_movk_i32 s71, 0x600
	s_movk_i32 s72, 0x81
	s_mov_b32 s73, 0x40c00000
	s_add_i32 s74, 0, 0x5000
	s_add_i32 s75, 0, 0xa000
	s_add_i32 s76, 0, 0xf000
	s_add_i32 s77, 0, 0x14000
	v_mov_b32_e32 v175, 0x400
	v_mov_b32_e32 v176, 0x60
	v_mov_b32_e32 v177, 0xf149f2ca
	s_branch .LBB0_423

.LBB0_437:
	s_and_b32 s10, 0xffff, s10
	v_mov_b32_e32 v34, v186
	s_lshl_b32 s10, s10, 12
	v_readfirstlane_b32 s52, v34
	s_lshl_b32 s53, s56, 2
	s_ashr_i32 s57, s52, 6
	s_lshl_b32 s60, s58, 1
	s_add_i32 s10, s54, s10
	s_add_i32 s54, s53, -2
	s_cmp_lg_u32 s56, 0
	s_cselect_b32 s59, s54, 0
	s_sub_i32 s62, s53, s59
	s_add_i32 s62, s62, 4
	v_lshlrev_b32_e32 v0, 3, v34
	v_and_b32_e32 v153, 63, v34
	s_mov_b32 s61, s39
	v_and_b32_e32 v134, 31, v153
	v_lshrrev_b32_e32 v135, 5, v153
	v_lshlrev_b32_e32 v132, 2, v135
	v_mov_b32_e32 v157, v132
	v_sub_u32_e32 v140, v134, v132
	v_lshrrev_b32_e32 v148, 1, v134
	v_and_b32_e32 v149, 6, v148
	v_lshlrev_b32_e32 v149, 4, v149
	v_and_b32_e32 v148, 1, v148
	v_xor_b32_e32 v148, v148, v135
	v_lshlrev_b32_e32 v148, 4, v148
	v_lshl_add_u32 v142, v134, 7, v149
	v_add_u32_e32 v142, v142, v148
	v_xor_b32_e32 v143, 32, v142
	v_xor_b32_e32 v144, 64, v142
	v_xor_b32_e32 v145, 0x60, v142
	v_bfe_u32 v148, v153, 4, 1
	v_lshlrev_b32_e32 v148, 5, v148
	v_and_b32_e32 v149, 3, v153
	v_lshl_add_u32 v148, v149, 3, v148
	v_bfe_u32 v149, v153, 2, 2
	v_add_u32_e32 v149, v149, v132
	v_lshl_add_u32 v146, v149, 6, v148
	s_lshl_b32 s78, s56, 8
	s_lshl_b32 s79, s57, 5
	s_add_i32 s78, s78, s79
	v_or_b32_e32 v148, s78, v134
	v_lshlrev_b32_e32 v148, s60, v148
	v_add_u32_e32 v130, s10, v148
	v_mov_b32_e32 v131, 0
	s_mul_i32 s80, s101, 0xc000
	s_mov_b32 s81, m0
	s_cmp_eq_u32 s100, s19
	s_cbranch_scc1 .Lk2_have
	s_lshl_b32 s95, s57, 3
	v_lshrrev_b32_e32 v148, 3, v153
	v_add_u32_e32 v148, s95, v148
	v_lshrrev_b32_e32 v149, 1, v148
	v_and_b32_e32 v150, 7, v153
	v_xor_b32_e32 v149, v149, v150
	v_and_b32_e32 v149, 7, v149
	v_lshlrev_b32_e32 v149, 4, v149
	s_lshl_b32 s95, s59, 6
	v_add_u32_e32 v148, s95, v148
	v_lshlrev_b32_e32 v148, s60, v148
	v_add_u32_e32 v148, s10, v148
	v_mov_b64_e32 v[150:151], s[40:41]
	v_mad_u64_u32 v[150:151], s[98:99], v148, s66, v[150:151]
	v_add_u32_e32 v148, 0x400, v149
	v_mov_b32_e32 v149, 0
	v_lshl_add_u64 v[150:151], v[150:151], 0, v[148:149]
	s_lshl_b32 s96, 0x60000, s60
	s_mov_b32 s97, 0
	s_lshl_b32 s95, s57, 10
	s_add_i32 s95, s95, s80
	s_add_i32 s85, s62, -1
	s_mov_b32 m0, s95
	s_nop 0
	global_load_lds_dwordx4 v[150:151], off
	s_cmp_le_u32 1, s85
	s_cbranch_scc0 .Lk2_own_k1
	v_lshl_add_u64 v[150:151], v[150:151], 0, s[96:97]
	s_addk_i32 s95, 0x2000
.Lk2_own_k1:
	s_mov_b32 m0, s95
	s_nop 0
	global_load_lds_dwordx4 v[150:151], off
	s_cmp_le_u32 2, s85
	s_cbranch_scc0 .Lk2_own_k2
	v_lshl_add_u64 v[150:151], v[150:151], 0, s[96:97]
	s_addk_i32 s95, 0x2000
.Lk2_own_k2:
	s_mov_b32 m0, s95
	s_nop 0
	global_load_lds_dwordx4 v[150:151], off
	s_cmp_le_u32 3, s85
	s_cbranch_scc0 .Lk2_own_k3
	v_lshl_add_u64 v[150:151], v[150:151], 0, s[96:97]
	s_addk_i32 s95, 0x2000
.Lk2_own_k3:
	s_mov_b32 m0, s95
	s_nop 0
	global_load_lds_dwordx4 v[150:151], off
	s_cmp_le_u32 4, s85
	s_cbranch_scc0 .Lk2_own_k4
	v_lshl_add_u64 v[150:151], v[150:151], 0, s[96:97]
	s_addk_i32 s95, 0x2000
.Lk2_own_k4:
	s_mov_b32 m0, s95
	s_nop 0
	global_load_lds_dwordx4 v[150:151], off
	s_cmp_le_u32 5, s85
	s_cbranch_scc0 .Lk2_own_k5
	v_lshl_add_u64 v[150:151], v[150:151], 0, s[96:97]
	s_addk_i32 s95, 0x2000
.Lk2_own_k5:
	s_mov_b32 m0, s95
	s_nop 0
	global_load_lds_dwordx4 v[150:151], off
	v_mov_b64_e32 v[150:151], s[40:41]
	v_mad_u64_u32 v[150:151], s[98:99], v130, s66, v[150:151]
	v_lshrrev_b32_e32 v148, 5, v153
	v_lshlrev_b32_e32 v148, 4, v148
	v_mov_b32_e32 v149, 0
	v_lshl_add_u64 v[150:151], v[150:151], 0, v[148:149]
	global_load_dwordx4 v[82:85], v[150:151], off
	global_load_dwordx4 v[86:89], v[150:151], off offset:32
	global_load_dwordx4 v[90:93], v[150:151], off offset:64
	global_load_dwordx4 v[94:97], v[150:151], off offset:96
.Lk2_have:
	s_waitcnt vmcnt(0)
	s_barrier
	s_cmp_eq_u32 s100, s19
	s_cbranch_scc0 .Lk2_noq
	v_mov_b32_e32 v82, v204
	v_mov_b32_e32 v83, v205
	v_mov_b32_e32 v84, v206
	v_mov_b32_e32 v85, v207
	v_mov_b32_e32 v86, v208
	v_mov_b32_e32 v87, v209
	v_mov_b32_e32 v88, v210
	v_mov_b32_e32 v89, v211
	v_mov_b32_e32 v90, v212
	v_mov_b32_e32 v91, v213
	v_mov_b32_e32 v92, v214
	v_mov_b32_e32 v93, v215
	v_mov_b32_e32 v94, v216
	v_mov_b32_e32 v95, v217
	v_mov_b32_e32 v96, v218
	v_mov_b32_e32 v97, v219
.Lk2_noq:
	s_and_b32 s95, s57, 3
	s_lshl_b32 s95, s95, 4
	v_lshrrev_b32_e32 v148, 2, v153
	v_add_u32_e32 v148, s95, v148
	s_lshl_b32 s95, s59, 6
	v_add_u32_e32 v148, s95, v148
	v_lshlrev_b32_e32 v148, s60, v148
	v_add_u32_e32 v148, s10, v148
	v_mov_b64_e32 v[150:151], s[40:41]
	v_mad_u64_u32 v[150:151], s[98:99], v148, s66, v[150:151]
	s_lshr_b32 s95, s57, 2
	s_lshl_b32 s95, s95, 6
	s_addk_i32 s95, 0x800
	v_and_b32_e32 v148, 3, v153
	v_lshl_add_u32 v148, v148, 4, s95
	v_mov_b32_e32 v149, 0
	v_lshl_add_u64 v[150:151], v[150:151], 0, v[148:149]
	s_lshl_b32 s96, 0x60000, s60
	s_mov_b32 s97, 0
	s_lshl_b32 s95, s57, 10
	s_add_i32 s95, s95, 0x18000
	s_add_i32 s85, s62, -1
	s_mov_b32 m0, s95
	s_nop 0
	global_load_lds_dwordx4 v[150:151], off
	s_cmp_le_u32 1, s85
	s_cbranch_scc0 .Lk2_cur_v1
	v_lshl_add_u64 v[150:151], v[150:151], 0, s[96:97]
	s_addk_i32 s95, 0x2000

.Lk2_cur_v3:
	s_mov_b32 m0, s95
	s_nop 0
	global_load_lds_dwordx4 v[150:151], off
	s_cmp_le_u32 4, s85
	s_cbranch_scc0 .Lk2_cur_v4
	v_lshl_add_u64 v[150:151], v[150:151], 0, s[96:97]
	s_addk_i32 s95, 0x6000

.Lk2_cur_v5:
	s_mov_b32 m0, s95
	s_nop 0
	global_load_lds_dwordx4 v[150:151], off
	s_mov_b32 s86, s19
	s_cmpk_lt_i32 s65, 0x80
	s_cbranch_scc1 .Lk2_idx
	s_cmpk_gt_i32 s65, 0x1ff
	s_cbranch_scc1 .Lk2_idx
	s_mov_b32 s86, s65
.Lk2_idx:
	s_mov_b32 s100, s86
	s_add_i32 s86, s86, 0xff80
	s_and_b32 s86, s86, 0xffff
	s_mul_i32 s87, s86, 0xaaab
	s_lshr_b32 s87, s87, 21
	s_mul_i32 s88, s87, 48
	s_sub_i32 s86, s86, s88
	s_lshl_b32 s87, s87, 12
	s_cmp_lt_u32 s86, 16
	s_cbranch_scc1 .Lk2_p0
	s_cmp_lt_u32 s86, 32
	s_cbranch_scc1 .Lk2_p1
	s_sub_i32 s88, s86, 32
	s_add_i32 s87, s87, s88
	s_mov_b32 s89, 0
	s_mov_b32 s90, 4
	s_branch .Lk2_dec
.Lk2_p0:
	s_mov_b32 s89, s86
	s_mov_b32 s90, 0
	s_branch .Lk2_dec
.Lk2_p1:
	s_sub_i32 s88, s86, 16
	s_lshr_b32 s88, s88, 2
	s_add_i32 s87, s87, s88
	s_and_b32 s89, s86, 3
	s_mov_b32 s90, 2
.Lk2_dec:
	s_lshl_b32 s91, s89, 2
	s_add_i32 s92, s91, -2
	s_cmp_lg_u32 s89, 0
	s_cselect_b32 s92, s92, 0
	s_sub_i32 s93, s91, s92
	s_add_i32 s93, s93, 4
	s_lshl_b32 s88, s89, 8
	s_add_i32 s88, s88, s79
	v_or_b32_e32 v136, s88, v134
	v_lshlrev_b32_e32 v136, s90, v136
	v_add_u32_e32 v136, s87, v136
	s_xor_b32 s94, s101, 1
	s_mul_i32 s94, s94, 0xc000
	s_lshl_b32 s95, s57, 3
	v_lshrrev_b32_e32 v148, 3, v153
	v_add_u32_e32 v148, s95, v148
	v_lshrrev_b32_e32 v149, 1, v148
	v_and_b32_e32 v150, 7, v153
	v_xor_b32_e32 v149, v149, v150
	v_and_b32_e32 v149, 7, v149
	v_lshlrev_b32_e32 v149, 4, v149
	s_lshl_b32 s95, s92, 6
	v_add_u32_e32 v148, s95, v148
	v_lshlrev_b32_e32 v148, s90, v148
	v_add_u32_e32 v148, s87, v148
	v_mov_b64_e32 v[150:151], s[40:41]
	v_mad_u64_u32 v[150:151], s[98:99], v148, s66, v[150:151]
	v_add_u32_e32 v148, 0x400, v149
	v_mov_b32_e32 v149, 0
	v_lshl_add_u64 v[150:151], v[150:151], 0, v[148:149]
	s_lshl_b32 s96, 0x60000, s90
	s_mov_b32 s97, 0
	s_lshl_b32 s95, s57, 10
	s_add_i32 s95, s95, s94
	s_add_i32 s85, s93, -1
	s_mov_b32 m0, s95
	s_nop 0
	global_load_lds_dwordx4 v[150:151], off
	s_cmp_le_u32 1, s85
	s_cbranch_scc0 .Lk2_nxt_k1
	v_lshl_add_u64 v[150:151], v[150:151], 0, s[96:97]
	s_addk_i32 s95, 0x2000

.Lk2_nxt_k5:
	s_mov_b32 m0, s95
	s_nop 0
	global_load_lds_dwordx4 v[150:151], off
	v_mov_b64_e32 v[150:151], s[40:41]
	v_mad_u64_u32 v[150:151], s[98:99], v136, s66, v[150:151]
	v_lshrrev_b32_e32 v148, 5, v153
	v_lshlrev_b32_e32 v148, 4, v148
	v_mov_b32_e32 v149, 0
	v_lshl_add_u64 v[150:151], v[150:151], 0, v[148:149]
	global_load_dwordx4 v[204:207], v[150:151], off
	global_load_dwordx4 v[208:211], v[150:151], off offset:32
	global_load_dwordx4 v[212:215], v[150:151], off offset:64
	global_load_dwordx4 v[216:219], v[150:151], off offset:96
	s_lshl_b32 s95, s93, 6
	s_add_i32 s95, s95, -1
	v_min_u32_e32 v148, s95, v186
	s_lshl_b32 s95, s92, 6
	v_add_u32_e32 v148, s95, v148
	v_lshlrev_b32_e32 v148, s90, v148
	v_add_u32_e32 v148, s87, v148
	v_mov_b64_e32 v[150:151], s[40:41]
	v_mad_u64_u32 v[150:151], s[98:99], v148, s66, v[150:151]
	global_load_dword v152, v[150:151], off offset:2048
	s_mov_b32 m0, s81
	s_add_i32 s61, s61, 1
	v_cvt_f32_i32_e32 v148, s61
	v_exp_f32_e64 v148, -v148
	s_lshl_b32 s53, 1, s60
	v_cvt_f32_ubyte0_e32 v149, s53
	s_nop 0
	v_mul_f32_e32 v148, v148, v149
	v_mul_f32_e32 v147, 0x3fb8aa3b, v148
	v_mov_b32_e32 v220, 0
	v_mov_b32_e32 v221, v147
	v_mul_f32_e32 v222, 0x40000000, v147
	v_mul_f32_e32 v223, 0x40400000, v147
	v_mul_f32_e32 v224, 0x41000000, v147
	v_mul_f32_e32 v225, 0x41100000, v147
	v_mul_f32_e32 v226, 0x41200000, v147
	v_mul_f32_e32 v227, 0x41300000, v147
	v_mul_f32_e32 v228, 0x41800000, v147
	v_mul_f32_e32 v229, 0x41880000, v147
	v_mul_f32_e32 v230, 0x41900000, v147
	v_mul_f32_e32 v231, 0x41980000, v147
	v_mul_f32_e32 v232, 0x41c00000, v147
	v_mul_f32_e32 v233, 0x41c80000, v147
	v_mul_f32_e32 v234, 0x41d00000, v147
	v_mul_f32_e32 v235, 0x41d80000, v147
	v_mov_b32_e32 v2, 0
	v_mov_b32_e32 v3, 0
	v_mov_b32_e32 v4, 0
	v_mov_b32_e32 v5, 0
	v_mov_b32_e32 v6, 0
	v_mov_b32_e32 v7, 0
	v_mov_b32_e32 v8, 0
	v_mov_b32_e32 v9, 0
	v_mov_b32_e32 v10, 0
	v_mov_b32_e32 v11, 0
	v_mov_b32_e32 v12, 0
	v_mov_b32_e32 v13, 0
	v_mov_b32_e32 v14, 0
	v_mov_b32_e32 v15, 0
	v_mov_b32_e32 v16, 0
	v_mov_b32_e32 v17, 0
	v_mov_b32_e32 v18, 0
	v_mov_b32_e32 v19, 0
	v_mov_b32_e32 v20, 0
	v_mov_b32_e32 v21, 0
	v_mov_b32_e32 v22, 0
	v_mov_b32_e32 v23, 0
	v_mov_b32_e32 v24, 0
	v_mov_b32_e32 v25, 0
	v_mov_b32_e32 v26, 0
	v_mov_b32_e32 v27, 0
	v_mov_b32_e32 v28, 0
	v_mov_b32_e32 v29, 0
	v_mov_b32_e32 v30, 0
	v_mov_b32_e32 v31, 0
	v_mov_b32_e32 v32, 0
	v_mov_b32_e32 v33, 0
	s_lshr_b32 s54, s78, 5
	s_sub_i32 s55, 4, s54
	s_max_i32 s55, s55, 0
	s_add_i32 s54, s54, -4
	s_add_i32 s52, s54, s55
	s_and_b32 s53, s52, 1
	s_lshr_b32 s52, s52, 1
	s_sub_i32 s52, s52, s59
	s_lshl_b32 s52, s52, 13
	s_lshl_b32 s53, s53, 12
	s_add_i32 s56, s53, s52
	s_add_i32 s56, s56, s80
	v_add_u32_e32 v148, s56, v142
	v_add_u32_e32 v149, s56, v143
	v_add_u32_e32 v150, s56, v144
	v_add_u32_e32 v151, s56, v145
	ds_read_b128 v[158:161], v148
	ds_read_b128 v[162:165], v149
	ds_read_b128 v[166:169], v150
	ds_read_b128 v[170:173], v151
	s_cmp_gt_u32 s55, 0
	s_cbranch_scc0 .Lk2_do0
	v_mov_b32_e32 v34, v177
	v_mov_b32_e32 v35, v177
	v_mov_b32_e32 v36, v177
	v_mov_b32_e32 v37, v177
	v_mov_b32_e32 v38, v177
	v_mov_b32_e32 v39, v177
	v_mov_b32_e32 v40, v177
	v_mov_b32_e32 v41, v177
	v_mov_b32_e32 v42, v177
	v_mov_b32_e32 v43, v177
	v_mov_b32_e32 v44, v177
	v_mov_b32_e32 v45, v177
	v_mov_b32_e32 v46, v177
	v_mov_b32_e32 v47, v177
	v_mov_b32_e32 v48, v177
	v_mov_b32_e32 v49, v177
	s_branch .Lk2_nx0
.Lk2_do0:
	v_add_u32_e32 v148, 128, v140
	v_cvt_f32_i32_e32 v148, v148
	v_mul_f32_e64 v141, -v147, v148
	v_add_f32_e32 v34, v220, v141
	v_add_f32_e32 v35, v221, v141
	v_add_f32_e32 v36, v222, v141
	v_add_f32_e32 v37, v223, v141
	v_add_f32_e32 v38, v224, v141
	v_add_f32_e32 v39, v225, v141
	v_add_f32_e32 v40, v226, v141
	v_add_f32_e32 v41, v227, v141
	v_add_f32_e32 v42, v228, v141
	v_add_f32_e32 v43, v229, v141
	v_add_f32_e32 v44, v230, v141
	v_add_f32_e32 v45, v231, v141
	v_add_f32_e32 v46, v232, v141
	v_add_f32_e32 v47, v233, v141
	v_add_f32_e32 v48, v234, v141
	v_add_f32_e32 v49, v235, v141
	v_cmp_lt_i32_e64 s[52:53], 0, v140
	v_cmp_lt_i32_e64 s[56:57], 1, v140
	v_cmp_lt_i32_e64 vcc, 2, v140
	v_cmp_lt_i32_e64 s[10:11], 3, v140
	s_nop 1
	v_cndmask_b32_e64 v34, v34, v177, s[52:53]
	v_cndmask_b32_e64 v35, v35, v177, s[56:57]
	v_cndmask_b32_e64 v36, v36, v177, vcc
	v_cndmask_b32_e64 v37, v37, v177, s[10:11]
	v_cmp_lt_i32_e64 s[52:53], 8, v140
	v_cmp_lt_i32_e64 s[56:57], 9, v140
	v_cmp_lt_i32_e64 vcc, 10, v140
	v_cmp_lt_i32_e64 s[10:11], 11, v140
	s_nop 1
	v_cndmask_b32_e64 v38, v38, v177, s[52:53]
	v_cndmask_b32_e64 v39, v39, v177, s[56:57]
	v_cndmask_b32_e64 v40, v40, v177, vcc
	v_cndmask_b32_e64 v41, v41, v177, s[10:11]
	v_cmp_lt_i32_e64 s[52:53], 16, v140
	v_cmp_lt_i32_e64 s[56:57], 17, v140
	v_cmp_lt_i32_e64 vcc, 18, v140
	v_cmp_lt_i32_e64 s[10:11], 19, v140
	s_nop 1
	v_cndmask_b32_e64 v42, v42, v177, s[52:53]
	v_cndmask_b32_e64 v43, v43, v177, s[56:57]
	v_cndmask_b32_e64 v44, v44, v177, vcc
	v_cndmask_b32_e64 v45, v45, v177, s[10:11]
	v_cmp_lt_i32_e64 s[52:53], 24, v140
	v_cmp_lt_i32_e64 s[56:57], 25, v140
	v_cmp_lt_i32_e64 vcc, 26, v140
	v_cmp_lt_i32_e64 s[10:11], 27, v140
	s_nop 1
	v_cndmask_b32_e64 v46, v46, v177, s[52:53]
	v_cndmask_b32_e64 v47, v47, v177, s[56:57]
	v_cndmask_b32_e64 v48, v48, v177, vcc
	v_cndmask_b32_e64 v49, v49, v177, s[10:11]
	s_mov_b32 s11, 0
	s_waitcnt lgkmcnt(0)
	s_nop 1
	v_mfma_f32_32x32x16_bf16 v[34:49], v[158:161], v[82:85], v[34:49]
	v_mfma_f32_32x32x16_bf16 v[34:49], v[162:165], v[86:89], v[34:49]
	v_mfma_f32_32x32x16_bf16 v[34:49], v[166:169], v[90:93], v[34:49]
	v_mfma_f32_32x32x16_bf16 v[34:49], v[170:173], v[94:97], v[34:49]
	s_add_i32 s52, s54, 1
	s_and_b32 s53, s52, 1
	s_lshr_b32 s52, s52, 1
	s_sub_i32 s52, s52, s59
	s_lshl_b32 s52, s52, 13
	s_lshl_b32 s53, s53, 12
	s_add_i32 s56, s53, s52
	s_add_i32 s56, s56, s80
	v_add_u32_e32 v148, s56, v142
	v_add_u32_e32 v149, s56, v143
	v_add_u32_e32 v150, s56, v144
	v_add_u32_e32 v151, s56, v145
	ds_read_b128 v[158:161], v148
	ds_read_b128 v[162:165], v149
	ds_read_b128 v[166:169], v150
	ds_read_b128 v[170:173], v151
.Lk2_nx0:
	s_cmp_gt_u32 s55, 1
	s_cbranch_scc0 .Lk2_do1
	v_mov_b32_e32 v50, v177
	v_mov_b32_e32 v51, v177
	v_mov_b32_e32 v52, v177
	v_mov_b32_e32 v53, v177
	v_mov_b32_e32 v54, v177
	v_mov_b32_e32 v55, v177
	v_mov_b32_e32 v56, v177
	v_mov_b32_e32 v57, v177
	v_mov_b32_e32 v58, v177
	v_mov_b32_e32 v59, v177
	v_mov_b32_e32 v60, v177
	v_mov_b32_e32 v61, v177
	v_mov_b32_e32 v62, v177
	v_mov_b32_e32 v63, v177
	v_mov_b32_e32 v64, v177
	v_mov_b32_e32 v65, v177
	s_branch .Lk2_nx1
.Lk2_do1:
	v_add_u32_e32 v148, 96, v140
	v_cvt_f32_i32_e32 v148, v148
	v_mul_f32_e64 v141, -v147, v148
	v_add_f32_e32 v50, v220, v141
	v_add_f32_e32 v51, v221, v141
	v_add_f32_e32 v52, v222, v141
	v_add_f32_e32 v53, v223, v141
	v_add_f32_e32 v54, v224, v141
	v_add_f32_e32 v55, v225, v141
	v_add_f32_e32 v56, v226, v141
	v_add_f32_e32 v57, v227, v141
	v_add_f32_e32 v58, v228, v141
	v_add_f32_e32 v59, v229, v141
	v_add_f32_e32 v60, v230, v141
	v_add_f32_e32 v61, v231, v141
	v_add_f32_e32 v62, v232, v141
	v_add_f32_e32 v63, v233, v141
	v_add_f32_e32 v64, v234, v141
	v_add_f32_e32 v65, v235, v141
	s_waitcnt lgkmcnt(0)
	s_nop 1
	v_mfma_f32_32x32x16_bf16 v[50:65], v[158:161], v[82:85], v[50:65]
	v_mfma_f32_32x32x16_bf16 v[50:65], v[162:165], v[86:89], v[50:65]
	v_mfma_f32_32x32x16_bf16 v[50:65], v[166:169], v[90:93], v[50:65]
	v_mfma_f32_32x32x16_bf16 v[50:65], v[170:173], v[94:97], v[50:65]
	s_add_i32 s52, s54, 2
	s_and_b32 s53, s52, 1
	s_lshr_b32 s52, s52, 1
	s_sub_i32 s52, s52, s59
	s_lshl_b32 s52, s52, 13
	s_lshl_b32 s53, s53, 12
	s_add_i32 s56, s53, s52
	s_add_i32 s56, s56, s80
	v_add_u32_e32 v148, s56, v142
	v_add_u32_e32 v149, s56, v143
	v_add_u32_e32 v150, s56, v144
	v_add_u32_e32 v151, s56, v145
	ds_read_b128 v[158:161], v148
	ds_read_b128 v[162:165], v149
	ds_read_b128 v[166:169], v150
	ds_read_b128 v[170:173], v151
.Lk2_nx1:
	s_cmp_gt_u32 s55, 2
	s_cbranch_scc0 .Lk2_do2
	v_mov_b32_e32 v66, v177
	v_mov_b32_e32 v67, v177
	v_mov_b32_e32 v68, v177
	v_mov_b32_e32 v69, v177
	v_mov_b32_e32 v70, v177
	v_mov_b32_e32 v71, v177
	v_mov_b32_e32 v72, v177
	v_mov_b32_e32 v73, v177
	v_mov_b32_e32 v74, v177
	v_mov_b32_e32 v75, v177
	v_mov_b32_e32 v76, v177
	v_mov_b32_e32 v77, v177
	v_mov_b32_e32 v78, v177
	v_mov_b32_e32 v79, v177
	v_mov_b32_e32 v80, v177
	v_mov_b32_e32 v81, v177
	s_branch .Lk2_nx2
.Lk2_do2:
	v_add_u32_e32 v148, 64, v140
	v_cvt_f32_i32_e32 v148, v148
	v_mul_f32_e64 v141, -v147, v148
	v_add_f32_e32 v66, v220, v141
	v_add_f32_e32 v67, v221, v141
	v_add_f32_e32 v68, v222, v141
	v_add_f32_e32 v69, v223, v141
	v_add_f32_e32 v70, v224, v141
	v_add_f32_e32 v71, v225, v141
	v_add_f32_e32 v72, v226, v141
	v_add_f32_e32 v73, v227, v141
	v_add_f32_e32 v74, v228, v141
	v_add_f32_e32 v75, v229, v141
	v_add_f32_e32 v76, v230, v141
	v_add_f32_e32 v77, v231, v141
	v_add_f32_e32 v78, v232, v141
	v_add_f32_e32 v79, v233, v141
	v_add_f32_e32 v80, v234, v141
	v_add_f32_e32 v81, v235, v141
	s_waitcnt lgkmcnt(0)
	s_nop 1
	v_mfma_f32_32x32x16_bf16 v[66:81], v[158:161], v[82:85], v[66:81]
	v_mfma_f32_32x32x16_bf16 v[66:81], v[162:165], v[86:89], v[66:81]
	v_mfma_f32_32x32x16_bf16 v[66:81], v[166:169], v[90:93], v[66:81]
	v_mfma_f32_32x32x16_bf16 v[66:81], v[170:173], v[94:97], v[66:81]
	s_add_i32 s52, s54, 3
	s_and_b32 s53, s52, 1
	s_lshr_b32 s52, s52, 1
	s_sub_i32 s52, s52, s59
	s_lshl_b32 s52, s52, 13
	s_lshl_b32 s53, s53, 12
	s_add_i32 s56, s53, s52
	s_add_i32 s56, s56, s80
	v_add_u32_e32 v148, s56, v142
	v_add_u32_e32 v149, s56, v143
	v_add_u32_e32 v150, s56, v144
	v_add_u32_e32 v151, s56, v145
	ds_read_b128 v[158:161], v148
	ds_read_b128 v[162:165], v149
	ds_read_b128 v[166:169], v150
	ds_read_b128 v[170:173], v151
.Lk2_nx2:
	s_cmp_gt_u32 s55, 3
	s_cbranch_scc0 .Lk2_do3
	v_mov_b32_e32 v98, v177
	v_mov_b32_e32 v99, v177
	v_mov_b32_e32 v100, v177
	v_mov_b32_e32 v101, v177
	v_mov_b32_e32 v102, v177
	v_mov_b32_e32 v103, v177
	v_mov_b32_e32 v104, v177
	v_mov_b32_e32 v105, v177
	v_mov_b32_e32 v106, v177
	v_mov_b32_e32 v107, v177
	v_mov_b32_e32 v108, v177
	v_mov_b32_e32 v109, v177
	v_mov_b32_e32 v110, v177
	v_mov_b32_e32 v111, v177
	v_mov_b32_e32 v112, v177
	v_mov_b32_e32 v113, v177
	s_branch .Lk2_nx3
.Lk2_do3:
	v_add_u32_e32 v148, 32, v140
	v_cvt_f32_i32_e32 v148, v148
	v_mul_f32_e64 v141, -v147, v148
	v_add_f32_e32 v98, v220, v141
	v_add_f32_e32 v99, v221, v141
	v_add_f32_e32 v100, v222, v141
	v_add_f32_e32 v101, v223, v141
	v_add_f32_e32 v102, v224, v141
	v_add_f32_e32 v103, v225, v141
	v_add_f32_e32 v104, v226, v141
	v_add_f32_e32 v105, v227, v141
	v_add_f32_e32 v106, v228, v141
	v_add_f32_e32 v107, v229, v141
	v_add_f32_e32 v108, v230, v141
	v_add_f32_e32 v109, v231, v141
	v_add_f32_e32 v110, v232, v141
	v_add_f32_e32 v111, v233, v141
	v_add_f32_e32 v112, v234, v141
	v_add_f32_e32 v113, v235, v141
	s_waitcnt lgkmcnt(0)
	s_nop 1
	v_mfma_f32_32x32x16_bf16 v[98:113], v[158:161], v[82:85], v[98:113]
	v_mfma_f32_32x32x16_bf16 v[98:113], v[162:165], v[86:89], v[98:113]
	v_mfma_f32_32x32x16_bf16 v[98:113], v[166:169], v[90:93], v[98:113]
	v_mfma_f32_32x32x16_bf16 v[98:113], v[170:173], v[94:97], v[98:113]
	s_add_i32 s52, s54, 4
	s_and_b32 s53, s52, 1
	s_lshr_b32 s52, s52, 1
	s_sub_i32 s52, s52, s59
	s_lshl_b32 s52, s52, 13
	s_lshl_b32 s53, s53, 12
	s_add_i32 s56, s53, s52
	s_add_i32 s56, s56, s80
	v_add_u32_e32 v148, s56, v142
	v_add_u32_e32 v149, s56, v143
	v_add_u32_e32 v150, s56, v144
	v_add_u32_e32 v151, s56, v145
	ds_read_b128 v[158:161], v148
	ds_read_b128 v[162:165], v149
	ds_read_b128 v[166:169], v150
	ds_read_b128 v[170:173], v151
.Lk2_nx3:
	s_cmp_gt_u32 s55, 4
	s_cbranch_scc0 .Lk2_do4
	v_mov_b32_e32 v114, v177
	v_mov_b32_e32 v115, v177
	v_mov_b32_e32 v116, v177
	v_mov_b32_e32 v117, v177
	v_mov_b32_e32 v118, v177
	v_mov_b32_e32 v119, v177
	v_mov_b32_e32 v120, v177
	v_mov_b32_e32 v121, v177
	v_mov_b32_e32 v122, v177
	v_mov_b32_e32 v123, v177
	v_mov_b32_e32 v124, v177
	v_mov_b32_e32 v125, v177
	v_mov_b32_e32 v126, v177
	v_mov_b32_e32 v127, v177
	v_mov_b32_e32 v128, v177
	v_mov_b32_e32 v129, v177
	s_branch .Lk2_nx4
.Lk2_do4:
	v_add_u32_e32 v148, 0, v140
	v_cvt_f32_i32_e32 v148, v148
	v_mul_f32_e64 v141, -v147, v148
	v_add_f32_e32 v114, v220, v141
	v_add_f32_e32 v115, v221, v141
	v_add_f32_e32 v116, v222, v141
	v_add_f32_e32 v117, v223, v141
	v_add_f32_e32 v118, v224, v141
	v_add_f32_e32 v119, v225, v141
	v_add_f32_e32 v120, v226, v141
	v_add_f32_e32 v121, v227, v141
	v_add_f32_e32 v122, v228, v141
	v_add_f32_e32 v123, v229, v141
	v_add_f32_e32 v124, v230, v141
	v_add_f32_e32 v125, v231, v141
	v_add_f32_e32 v126, v232, v141
	v_add_f32_e32 v127, v233, v141
	v_add_f32_e32 v128, v234, v141
	v_add_f32_e32 v129, v235, v141
	v_cmp_gt_i32_e64 s[52:53], 0, v140
	v_cmp_gt_i32_e64 s[56:57], 1, v140
	v_cmp_gt_i32_e64 vcc, 2, v140
	v_cmp_gt_i32_e64 s[10:11], 3, v140
	s_nop 1
	v_cndmask_b32_e64 v114, v114, v177, s[52:53]
	v_cndmask_b32_e64 v115, v115, v177, s[56:57]
	v_cndmask_b32_e64 v116, v116, v177, vcc
	v_cndmask_b32_e64 v117, v117, v177, s[10:11]
	v_cmp_gt_i32_e64 s[52:53], 8, v140
	v_cmp_gt_i32_e64 s[56:57], 9, v140
	v_cmp_gt_i32_e64 vcc, 10, v140
	v_cmp_gt_i32_e64 s[10:11], 11, v140
	s_nop 1
	v_cndmask_b32_e64 v118, v118, v177, s[52:53]
	v_cndmask_b32_e64 v119, v119, v177, s[56:57]
	v_cndmask_b32_e64 v120, v120, v177, vcc
	v_cndmask_b32_e64 v121, v121, v177, s[10:11]
	v_cmp_gt_i32_e64 s[52:53], 16, v140
	v_cmp_gt_i32_e64 s[56:57], 17, v140
	v_cmp_gt_i32_e64 vcc, 18, v140
	v_cmp_gt_i32_e64 s[10:11], 19, v140
	s_nop 1
	v_cndmask_b32_e64 v122, v122, v177, s[52:53]
	v_cndmask_b32_e64 v123, v123, v177, s[56:57]
	v_cndmask_b32_e64 v124, v124, v177, vcc
	v_cndmask_b32_e64 v125, v125, v177, s[10:11]
	v_cmp_gt_i32_e64 s[52:53], 24, v140
	v_cmp_gt_i32_e64 s[56:57], 25, v140
	v_cmp_gt_i32_e64 vcc, 26, v140
	v_cmp_gt_i32_e64 s[10:11], 27, v140
	s_nop 1
	v_cndmask_b32_e64 v126, v126, v177, s[52:53]
	v_cndmask_b32_e64 v127, v127, v177, s[56:57]
	v_cndmask_b32_e64 v128, v128, v177, vcc
	v_cndmask_b32_e64 v129, v129, v177, s[10:11]
	s_mov_b32 s11, 0
	s_waitcnt lgkmcnt(0)
	s_nop 1
	v_mfma_f32_32x32x16_bf16 v[114:129], v[158:161], v[82:85], v[114:129]
	v_mfma_f32_32x32x16_bf16 v[114:129], v[162:165], v[86:89], v[114:129]
	v_mfma_f32_32x32x16_bf16 v[114:129], v[166:169], v[90:93], v[114:129]
	v_mfma_f32_32x32x16_bf16 v[114:129], v[170:173], v[94:97], v[114:129]
.Lk2_nx4:
	s_nop 7
	s_nop 4
	v_max3_f32 v148, v34, v35, v36
	v_max3_f32 v149, v37, v38, v39
	v_max3_f32 v148, v148, v40, v41
	v_max3_f32 v149, v149, v42, v43
	v_max3_f32 v148, v148, v44, v45
	v_max3_f32 v149, v149, v46, v47
	v_max3_f32 v148, v148, v48, v49
	v_max3_f32 v149, v149, v50, v51
	v_max3_f32 v148, v148, v52, v53
	v_max3_f32 v149, v149, v54, v55
	v_max3_f32 v148, v148, v56, v57
	v_max3_f32 v149, v149, v58, v59
	v_max3_f32 v148, v148, v60, v61
	v_max3_f32 v149, v149, v62, v63
	v_max3_f32 v148, v148, v64, v65
	v_max3_f32 v149, v149, v66, v67
	v_max3_f32 v148, v148, v68, v69
	v_max3_f32 v149, v149, v70, v71
	v_max3_f32 v148, v148, v72, v73
	v_max3_f32 v149, v149, v74, v75
	v_max3_f32 v148, v148, v76, v77
	v_max3_f32 v149, v149, v78, v79
	v_max3_f32 v148, v148, v80, v81
	v_max3_f32 v149, v149, v98, v99
	v_max3_f32 v148, v148, v100, v101
	v_max3_f32 v149, v149, v102, v103
	v_max3_f32 v148, v148, v104, v105
	v_max3_f32 v149, v149, v106, v107
	v_max3_f32 v148, v148, v108, v109
	v_max3_f32 v149, v149, v110, v111
	v_max3_f32 v148, v148, v112, v113
	v_max3_f32 v149, v149, v114, v115
	v_max3_f32 v148, v148, v116, v117
	v_max3_f32 v149, v149, v118, v119
	v_max3_f32 v148, v148, v120, v121
	v_max3_f32 v149, v149, v122, v123
	v_max3_f32 v148, v148, v124, v125
	v_max3_f32 v149, v149, v126, v127
	v_max3_f32 v148, v148, v128, v129
	v_max_f32_e32 v148, v148, v149
	v_mov_b32_e32 v149, v148
	s_nop 1
	v_permlane32_swap_b32_e32 v148, v149
	v_max_f32_e32 v138, v148, v149
	v_sub_f32_e32 v34, v34, v138
	v_sub_f32_e32 v35, v35, v138
	v_sub_f32_e32 v36, v36, v138
	v_sub_f32_e32 v37, v37, v138
	v_sub_f32_e32 v38, v38, v138
	v_sub_f32_e32 v39, v39, v138
	v_sub_f32_e32 v40, v40, v138
	v_sub_f32_e32 v41, v41, v138
	v_sub_f32_e32 v42, v42, v138
	v_sub_f32_e32 v43, v43, v138
	v_sub_f32_e32 v44, v44, v138
	v_sub_f32_e32 v45, v45, v138
	v_sub_f32_e32 v46, v46, v138
	v_sub_f32_e32 v47, v47, v138
	v_sub_f32_e32 v48, v48, v138
	v_sub_f32_e32 v49, v49, v138
	v_sub_f32_e32 v50, v50, v138
	v_sub_f32_e32 v51, v51, v138
	v_sub_f32_e32 v52, v52, v138
	v_sub_f32_e32 v53, v53, v138
	v_sub_f32_e32 v54, v54, v138
	v_sub_f32_e32 v55, v55, v138
	v_sub_f32_e32 v56, v56, v138
	v_sub_f32_e32 v57, v57, v138
	v_sub_f32_e32 v58, v58, v138
	v_sub_f32_e32 v59, v59, v138
	v_sub_f32_e32 v60, v60, v138
	v_sub_f32_e32 v61, v61, v138
	v_sub_f32_e32 v62, v62, v138
	v_sub_f32_e32 v63, v63, v138
	v_sub_f32_e32 v64, v64, v138
	v_sub_f32_e32 v65, v65, v138
	v_sub_f32_e32 v66, v66, v138
	v_sub_f32_e32 v67, v67, v138
	v_sub_f32_e32 v68, v68, v138
	v_sub_f32_e32 v69, v69, v138
	v_sub_f32_e32 v70, v70, v138
	v_sub_f32_e32 v71, v71, v138
	v_sub_f32_e32 v72, v72, v138
	v_sub_f32_e32 v73, v73, v138
	v_sub_f32_e32 v74, v74, v138
	v_sub_f32_e32 v75, v75, v138
	v_sub_f32_e32 v76, v76, v138
	v_sub_f32_e32 v77, v77, v138
	v_sub_f32_e32 v78, v78, v138
	v_sub_f32_e32 v79, v79, v138
	v_sub_f32_e32 v80, v80, v138
	v_sub_f32_e32 v81, v81, v138
	v_sub_f32_e32 v98, v98, v138
	v_sub_f32_e32 v99, v99, v138
	v_sub_f32_e32 v100, v100, v138
	v_sub_f32_e32 v101, v101, v138
	v_sub_f32_e32 v102, v102, v138
	v_sub_f32_e32 v103, v103, v138
	v_sub_f32_e32 v104, v104, v138
	v_sub_f32_e32 v105, v105, v138
	v_sub_f32_e32 v106, v106, v138
	v_sub_f32_e32 v107, v107, v138
	v_sub_f32_e32 v108, v108, v138
	v_sub_f32_e32 v109, v109, v138
	v_sub_f32_e32 v110, v110, v138
	v_sub_f32_e32 v111, v111, v138
	v_sub_f32_e32 v112, v112, v138
	v_sub_f32_e32 v113, v113, v138
	v_sub_f32_e32 v114, v114, v138
	v_sub_f32_e32 v115, v115, v138
	v_sub_f32_e32 v116, v116, v138
	v_sub_f32_e32 v117, v117, v138
	v_sub_f32_e32 v118, v118, v138
	v_sub_f32_e32 v119, v119, v138
	v_sub_f32_e32 v120, v120, v138
	v_sub_f32_e32 v121, v121, v138
	v_sub_f32_e32 v122, v122, v138
	v_sub_f32_e32 v123, v123, v138
	v_sub_f32_e32 v124, v124, v138
	v_sub_f32_e32 v125, v125, v138
	v_sub_f32_e32 v126, v126, v138
	v_sub_f32_e32 v127, v127, v138
	v_sub_f32_e32 v128, v128, v138
	v_sub_f32_e32 v129, v129, v138
	v_exp_f32_e32 v34, v34
	v_exp_f32_e32 v35, v35
	v_exp_f32_e32 v36, v36
	v_exp_f32_e32 v37, v37
	v_exp_f32_e32 v38, v38
	v_exp_f32_e32 v39, v39
	v_exp_f32_e32 v40, v40
	v_exp_f32_e32 v41, v41
	v_exp_f32_e32 v42, v42
	v_exp_f32_e32 v43, v43
	v_exp_f32_e32 v44, v44
	v_exp_f32_e32 v45, v45
	v_exp_f32_e32 v46, v46
	v_exp_f32_e32 v47, v47
	v_exp_f32_e32 v48, v48
	v_exp_f32_e32 v49, v49
	v_exp_f32_e32 v50, v50
	v_exp_f32_e32 v51, v51
	v_exp_f32_e32 v52, v52
	v_exp_f32_e32 v53, v53
	v_exp_f32_e32 v54, v54
	v_exp_f32_e32 v55, v55
	v_exp_f32_e32 v56, v56
	v_exp_f32_e32 v57, v57
	v_exp_f32_e32 v58, v58
	v_exp_f32_e32 v59, v59
	v_exp_f32_e32 v60, v60
	v_exp_f32_e32 v61, v61
	v_exp_f32_e32 v62, v62
	v_exp_f32_e32 v63, v63
	v_exp_f32_e32 v64, v64
	v_exp_f32_e32 v65, v65
	v_exp_f32_e32 v66, v66
	v_exp_f32_e32 v67, v67
	v_exp_f32_e32 v68, v68
	v_exp_f32_e32 v69, v69
	v_exp_f32_e32 v70, v70
	v_exp_f32_e32 v71, v71
	v_exp_f32_e32 v72, v72
	v_exp_f32_e32 v73, v73
	v_exp_f32_e32 v74, v74
	v_exp_f32_e32 v75, v75
	v_exp_f32_e32 v76, v76
	v_exp_f32_e32 v77, v77
	v_exp_f32_e32 v78, v78
	v_exp_f32_e32 v79, v79
	v_exp_f32_e32 v80, v80
	v_exp_f32_e32 v81, v81
	v_exp_f32_e32 v98, v98
	v_exp_f32_e32 v99, v99
	v_exp_f32_e32 v100, v100
	v_exp_f32_e32 v101, v101
	v_exp_f32_e32 v102, v102
	v_exp_f32_e32 v103, v103
	v_exp_f32_e32 v104, v104
	v_exp_f32_e32 v105, v105
	v_exp_f32_e32 v106, v106
	v_exp_f32_e32 v107, v107
	v_exp_f32_e32 v108, v108
	v_exp_f32_e32 v109, v109
	v_exp_f32_e32 v110, v110
	v_exp_f32_e32 v111, v111
	v_exp_f32_e32 v112, v112
	v_exp_f32_e32 v113, v113
	v_exp_f32_e32 v114, v114
	v_exp_f32_e32 v115, v115
	v_exp_f32_e32 v116, v116
	v_exp_f32_e32 v117, v117
	v_exp_f32_e32 v118, v118
	v_exp_f32_e32 v119, v119
	v_exp_f32_e32 v120, v120
	v_exp_f32_e32 v121, v121
	v_exp_f32_e32 v122, v122
	v_exp_f32_e32 v123, v123
	v_exp_f32_e32 v124, v124
	v_exp_f32_e32 v125, v125
	v_exp_f32_e32 v126, v126
	v_exp_f32_e32 v127, v127
	v_exp_f32_e32 v128, v128
	v_exp_f32_e32 v129, v129
	v_add_f32_e32 v148, v34, v35
	v_add_f32_e32 v149, v36, v37
	v_add_f32_e32 v148, v148, v38
	v_add_f32_e32 v149, v149, v39
	v_add_f32_e32 v148, v148, v40
	v_add_f32_e32 v149, v149, v41
	v_add_f32_e32 v148, v148, v42
	v_add_f32_e32 v149, v149, v43
	v_add_f32_e32 v148, v148, v44
	v_add_f32_e32 v149, v149, v45
	v_add_f32_e32 v148, v148, v46
	v_add_f32_e32 v149, v149, v47
	v_add_f32_e32 v148, v148, v48
	v_add_f32_e32 v149, v149, v49
	v_add_f32_e32 v148, v148, v50
	v_add_f32_e32 v149, v149, v51
	v_add_f32_e32 v148, v148, v52
	v_add_f32_e32 v149, v149, v53
	v_add_f32_e32 v148, v148, v54
	v_add_f32_e32 v149, v149, v55
	v_add_f32_e32 v148, v148, v56
	v_add_f32_e32 v149, v149, v57
	v_add_f32_e32 v148, v148, v58
	v_add_f32_e32 v149, v149, v59
	v_add_f32_e32 v148, v148, v60
	v_add_f32_e32 v149, v149, v61
	v_add_f32_e32 v148, v148, v62
	v_add_f32_e32 v149, v149, v63
	v_add_f32_e32 v148, v148, v64
	v_add_f32_e32 v149, v149, v65
	v_add_f32_e32 v148, v148, v66
	v_add_f32_e32 v149, v149, v67
	v_add_f32_e32 v148, v148, v68
	v_add_f32_e32 v149, v149, v69
	v_add_f32_e32 v148, v148, v70
	v_add_f32_e32 v149, v149, v71
	v_add_f32_e32 v148, v148, v72
	v_add_f32_e32 v149, v149, v73
	v_add_f32_e32 v148, v148, v74
	v_add_f32_e32 v149, v149, v75
	v_add_f32_e32 v148, v148, v76
	v_add_f32_e32 v149, v149, v77
	v_add_f32_e32 v148, v148, v78
	v_add_f32_e32 v149, v149, v79
	v_add_f32_e32 v148, v148, v80
	v_add_f32_e32 v149, v149, v81
	v_add_f32_e32 v148, v148, v98
	v_add_f32_e32 v149, v149, v99
	v_add_f32_e32 v148, v148, v100
	v_add_f32_e32 v149, v149, v101
	v_add_f32_e32 v148, v148, v102
	v_add_f32_e32 v149, v149, v103
	v_add_f32_e32 v148, v148, v104
	v_add_f32_e32 v149, v149, v105
	v_add_f32_e32 v148, v148, v106
	v_add_f32_e32 v149, v149, v107
	v_add_f32_e32 v148, v148, v108
	v_add_f32_e32 v149, v149, v109
	v_add_f32_e32 v148, v148, v110
	v_add_f32_e32 v149, v149, v111
	v_add_f32_e32 v148, v148, v112
	v_add_f32_e32 v149, v149, v113
	v_add_f32_e32 v148, v148, v114
	v_add_f32_e32 v149, v149, v115
	v_add_f32_e32 v148, v148, v116
	v_add_f32_e32 v149, v149, v117
	v_add_f32_e32 v148, v148, v118
	v_add_f32_e32 v149, v149, v119
	v_add_f32_e32 v148, v148, v120
	v_add_f32_e32 v149, v149, v121
	v_add_f32_e32 v148, v148, v122
	v_add_f32_e32 v149, v149, v123
	v_add_f32_e32 v148, v148, v124
	v_add_f32_e32 v149, v149, v125
	v_add_f32_e32 v148, v148, v126
	v_add_f32_e32 v149, v149, v127
	v_add_f32_e32 v148, v148, v128
	v_add_f32_e32 v149, v149, v129
	v_add_f32_e32 v139, v148, v149
	v_cvt_pk_bf16_f32 v34, v34, v35
	v_cvt_pk_bf16_f32 v35, v36, v37
	v_cvt_pk_bf16_f32 v36, v38, v39
	v_cvt_pk_bf16_f32 v37, v40, v41
	v_cvt_pk_bf16_f32 v38, v42, v43
	v_cvt_pk_bf16_f32 v39, v44, v45
	v_cvt_pk_bf16_f32 v40, v46, v47
	v_cvt_pk_bf16_f32 v41, v48, v49
	v_cvt_pk_bf16_f32 v50, v50, v51
	v_cvt_pk_bf16_f32 v51, v52, v53
	v_cvt_pk_bf16_f32 v52, v54, v55
	v_cvt_pk_bf16_f32 v53, v56, v57
	v_cvt_pk_bf16_f32 v54, v58, v59
	v_cvt_pk_bf16_f32 v55, v60, v61
	v_cvt_pk_bf16_f32 v56, v62, v63
	v_cvt_pk_bf16_f32 v57, v64, v65
	v_cvt_pk_bf16_f32 v66, v66, v67
	v_cvt_pk_bf16_f32 v67, v68, v69
	v_cvt_pk_bf16_f32 v68, v70, v71
	v_cvt_pk_bf16_f32 v69, v72, v73
	v_cvt_pk_bf16_f32 v70, v74, v75
	v_cvt_pk_bf16_f32 v71, v76, v77
	v_cvt_pk_bf16_f32 v72, v78, v79
	v_cvt_pk_bf16_f32 v73, v80, v81
	v_cvt_pk_bf16_f32 v98, v98, v99
	v_cvt_pk_bf16_f32 v99, v100, v101
	v_cvt_pk_bf16_f32 v100, v102, v103
	v_cvt_pk_bf16_f32 v101, v104, v105
	v_cvt_pk_bf16_f32 v102, v106, v107
	v_cvt_pk_bf16_f32 v103, v108, v109
	v_cvt_pk_bf16_f32 v104, v110, v111
	v_cvt_pk_bf16_f32 v105, v112, v113
	v_cvt_pk_bf16_f32 v114, v114, v115
	v_cvt_pk_bf16_f32 v115, v116, v117
	v_cvt_pk_bf16_f32 v116, v118, v119
	v_cvt_pk_bf16_f32 v117, v120, v121
	v_cvt_pk_bf16_f32 v118, v122, v123
	v_cvt_pk_bf16_f32 v119, v124, v125
	v_cvt_pk_bf16_f32 v120, v126, v127
	v_cvt_pk_bf16_f32 v121, v128, v129
	s_waitcnt vmcnt(11)
	s_barrier
	s_cmp_gt_u32 s55, 0
	s_cbranch_scc1 .Lk2_pv0
	s_add_i32 s52, s54, 0
	s_and_b32 s53, s52, 1
	s_lshr_b32 s52, s52, 1
	s_sub_i32 s52, s52, s59
	s_cmp_gt_u32 s52, 3
	s_cselect_b32 s56, 0x4000, 0
	s_lshl_b32 s52, s52, 13
	s_lshl_b32 s53, s53, 11
	s_add_i32 s53, s53, s52
	s_add_i32 s53, s53, s56
	s_add_i32 s53, s53, 0x18000
	v_add_u32_e32 v148, s53, v146
	ds_read_b64_tr_b16 v[188:189], v148
	ds_read_b64_tr_b16 v[190:191], v148 offset:512
	ds_read_b64_tr_b16 v[192:193], v148 offset:1024
	ds_read_b64_tr_b16 v[194:195], v148 offset:1536
	ds_read_b64_tr_b16 v[196:197], v148 offset:4096
	ds_read_b64_tr_b16 v[198:199], v148 offset:4608
	ds_read_b64_tr_b16 v[200:201], v148 offset:5120
	ds_read_b64_tr_b16 v[202:203], v148 offset:5632
	s_waitcnt lgkmcnt(0)
	s_nop 1
	v_mfma_f32_32x32x16_bf16 v[18:33], v[188:191], v[34:37], v[18:33]
	v_mfma_f32_32x32x16_bf16 v[2:17], v[196:199], v[34:37], v[2:17]
	v_mfma_f32_32x32x16_bf16 v[18:33], v[192:195], v[38:41], v[18:33]
	v_mfma_f32_32x32x16_bf16 v[2:17], v[200:203], v[38:41], v[2:17]
.Lk2_pv0:
	s_cmp_gt_u32 s55, 1
	s_cbranch_scc1 .Lk2_pv1
	s_add_i32 s52, s54, 1
	s_and_b32 s53, s52, 1
	s_lshr_b32 s52, s52, 1
	s_sub_i32 s52, s52, s59
	s_cmp_gt_u32 s52, 3
	s_cselect_b32 s56, 0x4000, 0
	s_lshl_b32 s52, s52, 13
	s_lshl_b32 s53, s53, 11
	s_add_i32 s53, s53, s52
	s_add_i32 s53, s53, s56
	s_add_i32 s53, s53, 0x18000
	v_add_u32_e32 v148, s53, v146
	ds_read_b64_tr_b16 v[188:189], v148
	ds_read_b64_tr_b16 v[190:191], v148 offset:512
	ds_read_b64_tr_b16 v[192:193], v148 offset:1024
	ds_read_b64_tr_b16 v[194:195], v148 offset:1536
	ds_read_b64_tr_b16 v[196:197], v148 offset:4096
	ds_read_b64_tr_b16 v[198:199], v148 offset:4608
	ds_read_b64_tr_b16 v[200:201], v148 offset:5120
	ds_read_b64_tr_b16 v[202:203], v148 offset:5632
	s_waitcnt lgkmcnt(0)
	s_nop 1
	v_mfma_f32_32x32x16_bf16 v[18:33], v[188:191], v[50:53], v[18:33]
	v_mfma_f32_32x32x16_bf16 v[2:17], v[196:199], v[50:53], v[2:17]
	v_mfma_f32_32x32x16_bf16 v[18:33], v[192:195], v[54:57], v[18:33]
	v_mfma_f32_32x32x16_bf16 v[2:17], v[200:203], v[54:57], v[2:17]
.Lk2_pv1:
	s_cmp_gt_u32 s55, 2
	s_cbranch_scc1 .Lk2_pv2
	s_add_i32 s52, s54, 2
	s_and_b32 s53, s52, 1
	s_lshr_b32 s52, s52, 1
	s_sub_i32 s52, s52, s59
	s_cmp_gt_u32 s52, 3
	s_cselect_b32 s56, 0x4000, 0
	s_lshl_b32 s52, s52, 13
	s_lshl_b32 s53, s53, 11
	s_add_i32 s53, s53, s52
	s_add_i32 s53, s53, s56
	s_add_i32 s53, s53, 0x18000
	v_add_u32_e32 v148, s53, v146
	ds_read_b64_tr_b16 v[188:189], v148
	ds_read_b64_tr_b16 v[190:191], v148 offset:512
	ds_read_b64_tr_b16 v[192:193], v148 offset:1024
	ds_read_b64_tr_b16 v[194:195], v148 offset:1536
	ds_read_b64_tr_b16 v[196:197], v148 offset:4096
	ds_read_b64_tr_b16 v[198:199], v148 offset:4608
	ds_read_b64_tr_b16 v[200:201], v148 offset:5120
	ds_read_b64_tr_b16 v[202:203], v148 offset:5632
	s_waitcnt lgkmcnt(0)
	s_nop 1
	v_mfma_f32_32x32x16_bf16 v[18:33], v[188:191], v[66:69], v[18:33]
	v_mfma_f32_32x32x16_bf16 v[2:17], v[196:199], v[66:69], v[2:17]
	v_mfma_f32_32x32x16_bf16 v[18:33], v[192:195], v[70:73], v[18:33]
	v_mfma_f32_32x32x16_bf16 v[2:17], v[200:203], v[70:73], v[2:17]
.Lk2_pv2:
	s_cmp_gt_u32 s55, 3
	s_cbranch_scc1 .Lk2_pv3
	s_add_i32 s52, s54, 3
	s_and_b32 s53, s52, 1
	s_lshr_b32 s52, s52, 1
	s_sub_i32 s52, s52, s59
	s_cmp_gt_u32 s52, 3
	s_cselect_b32 s56, 0x4000, 0
	s_lshl_b32 s52, s52, 13
	s_lshl_b32 s53, s53, 11
	s_add_i32 s53, s53, s52
	s_add_i32 s53, s53, s56
	s_add_i32 s53, s53, 0x18000
	v_add_u32_e32 v148, s53, v146
	ds_read_b64_tr_b16 v[188:189], v148
	ds_read_b64_tr_b16 v[190:191], v148 offset:512
	ds_read_b64_tr_b16 v[192:193], v148 offset:1024
	ds_read_b64_tr_b16 v[194:195], v148 offset:1536
	ds_read_b64_tr_b16 v[196:197], v148 offset:4096
	ds_read_b64_tr_b16 v[198:199], v148 offset:4608
	ds_read_b64_tr_b16 v[200:201], v148 offset:5120
	ds_read_b64_tr_b16 v[202:203], v148 offset:5632
	s_waitcnt lgkmcnt(0)
	s_nop 1
	v_mfma_f32_32x32x16_bf16 v[18:33], v[188:191], v[98:101], v[18:33]
	v_mfma_f32_32x32x16_bf16 v[2:17], v[196:199], v[98:101], v[2:17]
	v_mfma_f32_32x32x16_bf16 v[18:33], v[192:195], v[102:105], v[18:33]
	v_mfma_f32_32x32x16_bf16 v[2:17], v[200:203], v[102:105], v[2:17]
.Lk2_pv3:
	s_cmp_gt_u32 s55, 4
	s_cbranch_scc1 .Lk2_pv4
	s_add_i32 s52, s54, 4
	s_and_b32 s53, s52, 1
	s_lshr_b32 s52, s52, 1
	s_sub_i32 s52, s52, s59
	s_cmp_gt_u32 s52, 3
	s_cselect_b32 s56, 0x4000, 0
	s_lshl_b32 s52, s52, 13
	s_lshl_b32 s53, s53, 11
	s_add_i32 s53, s53, s52
	s_add_i32 s53, s53, s56
	s_add_i32 s53, s53, 0x18000
	v_add_u32_e32 v148, s53, v146
	ds_read_b64_tr_b16 v[188:189], v148
	ds_read_b64_tr_b16 v[190:191], v148 offset:512
	ds_read_b64_tr_b16 v[192:193], v148 offset:1024
	ds_read_b64_tr_b16 v[194:195], v148 offset:1536
	ds_read_b64_tr_b16 v[196:197], v148 offset:4096
	ds_read_b64_tr_b16 v[198:199], v148 offset:4608
	ds_read_b64_tr_b16 v[200:201], v148 offset:5120
	ds_read_b64_tr_b16 v[202:203], v148 offset:5632
	s_waitcnt lgkmcnt(0)
	s_nop 1
	v_mfma_f32_32x32x16_bf16 v[18:33], v[188:191], v[114:117], v[18:33]
	v_mfma_f32_32x32x16_bf16 v[2:17], v[196:199], v[114:117], v[2:17]
	v_mfma_f32_32x32x16_bf16 v[18:33], v[192:195], v[118:121], v[18:33]
	v_mfma_f32_32x32x16_bf16 v[2:17], v[200:203], v[118:121], v[2:17]
.Lk2_pv4:
	s_xor_b32 s101, s101, 1
	s_nop 7
	s_nop 7

	.amdhsa_kernel _Z8fwd_mega4Args
		.amdhsa_group_segment_fixed_size 16384
		.amdhsa_private_segment_fixed_size 0
		.amdhsa_kernarg_size 344
		.amdhsa_user_sgpr_count 2
		.amdhsa_user_sgpr_dispatch_ptr 0
		.amdhsa_user_sgpr_queue_ptr 0
		.amdhsa_user_sgpr_kernarg_segment_ptr 1
		.amdhsa_user_sgpr_dispatch_id 0
		.amdhsa_user_sgpr_kernarg_preload_length 0
		.amdhsa_user_sgpr_kernarg_preload_offset 0
		.amdhsa_user_sgpr_private_segment_size 0
		.amdhsa_uses_dynamic_stack 0
		.amdhsa_enable_private_segment 0
		.amdhsa_system_sgpr_workgroup_id_x 1
		.amdhsa_system_sgpr_workgroup_id_y 0
		.amdhsa_system_sgpr_workgroup_id_z 0
		.amdhsa_system_sgpr_workgroup_info 0
		.amdhsa_system_vgpr_workitem_id 2
		.amdhsa_next_free_vgpr 240
		.amdhsa_next_free_sgpr 102
		.amdhsa_accum_offset 240
		.amdhsa_reserve_vcc 1
		.amdhsa_float_round_mode_32 0
		.amdhsa_float_round_mode_16_64 0
		.amdhsa_float_denorm_mode_32 3
		.amdhsa_float_denorm_mode_16_64 3
		.amdhsa_dx10_clamp 1
		.amdhsa_ieee_mode 1
		.amdhsa_fp16_overflow 0
		.amdhsa_tg_split 0
		.amdhsa_exception_fp_ieee_invalid_op 0
		.amdhsa_exception_fp_denorm_src 0
		.amdhsa_exception_fp_ieee_div_zero 0
		.amdhsa_exception_fp_ieee_overflow 0
		.amdhsa_exception_fp_ieee_underflow 0
		.amdhsa_exception_fp_ieee_inexact 0
		.amdhsa_exception_int_div_zero 0
	.end_amdhsa_kernel

amdhsa.kernels:
  - .agpr_count:     0
    .args:
      - .offset:         0
        .size:           88
        .value_kind:     by_value
      - .offset:         88
        .size:           4
        .value_kind:     hidden_block_count_x
      - .offset:         92
        .size:           4
        .value_kind:     hidden_block_count_y
      - .offset:         96
        .size:           4
        .value_kind:     hidden_block_count_z
      - .offset:         100
        .size:           2
        .value_kind:     hidden_group_size_x
      - .offset:         102
        .size:           2
        .value_kind:     hidden_group_size_y
      - .offset:         104
        .size:           2
        .value_kind:     hidden_group_size_z
      - .offset:         106
        .size:           2
        .value_kind:     hidden_remainder_x
      - .offset:         108
        .size:           2
        .value_kind:     hidden_remainder_y
      - .offset:         110
        .size:           2
        .value_kind:     hidden_remainder_z
      - .offset:         128
        .size:           8
        .value_kind:     hidden_global_offset_x
      - .offset:         136
        .size:           8
        .value_kind:     hidden_global_offset_y
      - .offset:         144
        .size:           8
        .value_kind:     hidden_global_offset_z
      - .offset:         152
        .size:           2
        .value_kind:     hidden_grid_dims
      - .offset:         176
        .size:           8
        .value_kind:     hidden_multigrid_sync_arg
      - .offset:         208
        .size:           4
        .value_kind:     hidden_dynamic_lds_size
    .group_segment_fixed_size: 16384
    .kernarg_segment_align: 8
    .kernarg_segment_size: 344
    .language:       OpenCL C
    .language_version:
      - 2
      - 0
    .max_flat_workgroup_size: 512
    .name:           _Z8fwd_mega4Args
    .private_segment_fixed_size: 0
    .sgpr_count:     108
    .sgpr_spill_count: 1
    .symbol:         _Z8fwd_mega4Args.kd
    .uniform_work_group_size: 1
    .uses_dynamic_stack: false
    .vgpr_count:     240
    .vgpr_spill_count: 0
    .wavefront_size: 64
